# MFMA-to-VALU pad before the row-max chain trimmed to the required 12 wait states (s_nop 8 + the two scalar test instructions)
# baseline (speedup 1.0000x reference)
.LBB0_885:
	s_nop 8
	s_cmp_lg_u64 s[64:65], 0
	s_cbranch_scc1 .Lhwat0_full
	v_max_f32_e32 v203, v80, v81
	v_max_f32_e32 v205, v64, v65
	v_max3_f32 v203, v203, v82, v83
	v_max3_f32 v205, v205, v66, v67
	v_max3_f32 v203, v203, v84, v85
	v_max3_f32 v205, v205, v68, v69
	v_max3_f32 v203, v203, v86, v87
	v_max3_f32 v205, v205, v70, v71
	v_max3_f32 v203, v203, v88, v89
	v_max3_f32 v205, v205, v72, v73
	v_max3_f32 v203, v203, v90, v91
	v_max3_f32 v205, v205, v74, v75
	v_max3_f32 v203, v203, v92, v93
	v_max3_f32 v205, v205, v76, v77
	v_max3_f32 v203, v203, v94, v95
	v_max3_f32 v205, v205, v78, v79
	v_max_f32_e32 v204, v203, v205
	v_cmp_lt_f32_e32 vcc, s83, v204
	s_cbranch_vccz .LBB0_887

.LBB0_2119:
	s_nop 8
	s_cmp_lg_u64 s[64:65], 0
	s_cbranch_scc1 .Lhwat1_full
	v_max_f32_e32 v203, v80, v81
	v_max_f32_e32 v205, v64, v65
	v_max3_f32 v203, v203, v82, v83
	v_max3_f32 v205, v205, v66, v67
	v_max3_f32 v203, v203, v84, v85
	v_max3_f32 v205, v205, v68, v69
	v_max3_f32 v203, v203, v86, v87
	v_max3_f32 v205, v205, v70, v71
	v_max3_f32 v203, v203, v88, v89
	v_max3_f32 v205, v205, v72, v73
	v_max3_f32 v203, v203, v90, v91
	v_max3_f32 v205, v205, v74, v75
	v_max3_f32 v203, v203, v92, v93
	v_max3_f32 v205, v205, v76, v77
	v_max3_f32 v203, v203, v94, v95
	v_max3_f32 v205, v205, v78, v79
	v_max_f32_e32 v204, v203, v205
	v_cmp_lt_f32_e32 vcc, s82, v204
	s_cbranch_vccz .LBB0_2121
